# gate-weight transpose into LDS with all 16 loads per thread in flight (LN + gate-logit phases), on top of the loop-edge edits
# speedup vs baseline: 1.0067x; 1.0067x over previous
; __device__ __forceinline__ int mk_tid(int wv) { return (wv << 6) | lane_now(); }
; #define LAS __attribute__((address_space(3)))
; template <int SRC, int EXTRA, bool OUT8 = false> ...
;     const int tid = mk_tid(wv); const int lane = tid & 63, wave = wv;
;     LAS float* w8s = (LAS float*)lds;
;     LAS unsigned* lcnt = (LAS unsigned*)(lds + 32768);
;     if (EXTRA != 0) { for (int i = tid; i < 8192; i += NT) { const int k = i >> 3, j = i & 7; w8s[j * 1024 + k] = w8[(size_t)k * w8ld + j]; } if (tid < 8) lcnt[tid] = 0u; __syncthreads(); }
.LBB0_41:
	s_mov_b64 s[4:5], s[0:1]
	s_barrier
	s_load_dwordx2 s[22:23], s[4:5], 0x0
	s_mov_b64 s[4:5], s[0:1]
	s_mov_b64 s[6:7], s[0:1]
	s_load_dwordx2 s[4:5], s[4:5], 0x8
	s_load_dwordx2 s[8:9], s[6:7], 0x10
	s_mov_b64 s[6:7], s[0:1]
	s_mov_b64 s[10:11], s[0:1]
	s_load_dwordx2 s[6:7], s[6:7], 0xc0
	s_load_dwordx2 s[36:37], s[10:11], 0xc0
	s_mov_b64 s[14:15], s[0:1]
	s_mov_b64 s[10:11], s[0:1]
	s_mov_b64 s[12:13], s[0:1]
	s_load_dwordx2 s[10:11], s[10:11], 0x20
	s_load_dwordx2 s[28:29], s[12:13], 0xc0
	v_mbcnt_lo_u32_b32 v8, -1, 0
	v_mbcnt_hi_u32_b32 v8, -1, v8
	s_movk_i32 s3, 0x2000
	v_or_b32_e32 v2, s69, v8
	v_cmp_gt_i32_e32 vcc, s3, v2
	s_and_saveexec_b64 s[12:13], vcc
	s_cbranch_execz .LBB0_53
	s_load_dwordx2 s[14:15], s[14:15], 0x18
	v_and_b32_e32 v3, 7, v8
	v_lshlrev_b32_e32 v4, 2, v3
	v_lshl_add_u32 v9, v3, 12, 0
	v_max_i32_e32 v3, 0x1e00, v2
	v_mov_b32_e32 v5, 0
	v_sub_u32_e32 v3, v3, v2
	s_waitcnt lgkmcnt(0)
	v_lshl_add_u64 v[4:5], s[14:15], 0, v[4:5]
	s_mov_b64 s[14:15], 0x1800
	s_movk_i32 s3, 0x1ff
	v_add_u32_e32 v6, 0x1ff, v3
	v_lshl_add_u64 v[4:5], v[4:5], 0, s[14:15]
	v_ashrrev_i32_e32 v100, 3, v2
	v_mul_u32_u24_e32 v102, 0x5020, v100
	v_mov_b32_e32 v103, 0
	v_lshl_add_u64 v[104:105], v[4:5], 0, v[102:103]
	s_mov_b32 s14, 0x140800
	s_mov_b32 s15, 0
	global_load_dword v110, v[104:105], off
	v_lshl_add_u64 v[104:105], v[104:105], 0, s[14:15]
	global_load_dword v111, v[104:105], off
	v_lshl_add_u64 v[104:105], v[104:105], 0, s[14:15]
	global_load_dword v112, v[104:105], off
	v_lshl_add_u64 v[104:105], v[104:105], 0, s[14:15]
	global_load_dword v113, v[104:105], off
	v_lshl_add_u64 v[104:105], v[104:105], 0, s[14:15]
	global_load_dword v114, v[104:105], off
	v_lshl_add_u64 v[104:105], v[104:105], 0, s[14:15]
	global_load_dword v115, v[104:105], off
	v_lshl_add_u64 v[104:105], v[104:105], 0, s[14:15]
	global_load_dword v116, v[104:105], off
	v_lshl_add_u64 v[104:105], v[104:105], 0, s[14:15]
	global_load_dword v117, v[104:105], off
	v_lshl_add_u64 v[104:105], v[104:105], 0, s[14:15]
	global_load_dword v118, v[104:105], off
	v_lshl_add_u64 v[104:105], v[104:105], 0, s[14:15]
	global_load_dword v119, v[104:105], off
	v_lshl_add_u64 v[104:105], v[104:105], 0, s[14:15]
	global_load_dword v120, v[104:105], off
	v_lshl_add_u64 v[104:105], v[104:105], 0, s[14:15]
	global_load_dword v121, v[104:105], off
	v_lshl_add_u64 v[104:105], v[104:105], 0, s[14:15]
	global_load_dword v122, v[104:105], off
	v_lshl_add_u64 v[104:105], v[104:105], 0, s[14:15]
	global_load_dword v123, v[104:105], off
	v_lshl_add_u64 v[104:105], v[104:105], 0, s[14:15]
	global_load_dword v124, v[104:105], off
	v_lshl_add_u64 v[104:105], v[104:105], 0, s[14:15]
	global_load_dword v125, v[104:105], off
	v_lshl_add_u32 v101, v100, 2, v9
	s_waitcnt vmcnt(15)
	ds_write_b32 v101, v110
	s_waitcnt vmcnt(14)
	ds_write_b32 v101, v111 offset:256
	s_waitcnt vmcnt(13)
	ds_write_b32 v101, v112 offset:512
	s_waitcnt vmcnt(12)
	ds_write_b32 v101, v113 offset:768
	s_waitcnt vmcnt(11)
	ds_write_b32 v101, v114 offset:1024
	s_waitcnt vmcnt(10)
	ds_write_b32 v101, v115 offset:1280
	s_waitcnt vmcnt(9)
	ds_write_b32 v101, v116 offset:1536
	s_waitcnt vmcnt(8)
	ds_write_b32 v101, v117 offset:1792
	s_waitcnt vmcnt(7)
	ds_write_b32 v101, v118 offset:2048
	s_waitcnt vmcnt(6)
	ds_write_b32 v101, v119 offset:2304
	s_waitcnt vmcnt(5)
	ds_write_b32 v101, v120 offset:2560
	s_waitcnt vmcnt(4)
	ds_write_b32 v101, v121 offset:2816
	s_waitcnt vmcnt(3)
	ds_write_b32 v101, v122 offset:3072
	s_waitcnt vmcnt(2)
	ds_write_b32 v101, v123 offset:3328
	s_waitcnt vmcnt(1)
	ds_write_b32 v101, v124 offset:3584
	s_waitcnt vmcnt(0)
	ds_write_b32 v101, v125 offset:3840

; __device__ __forceinline__ int mk_tid(int wv) { return (wv << 6) | lane_now(); }
; #define LAS __attribute__((address_space(3)))
; template <int SRC, int EXTRA, bool OUT8 = false> ...
;     const int tid = mk_tid(wv); const int lane = tid & 63, wave = wv;
;     LAS float* w8s = (LAS float*)lds;
;     LAS unsigned* lcnt = (LAS unsigned*)(lds + 32768);
;     if (EXTRA != 0) { for (int i = tid; i < 8192; i += NT) { const int k = i >> 3, j = i & 7; w8s[j * 1024 + k] = w8[(size_t)k * w8ld + j]; } if (tid < 8) lcnt[tid] = 0u; __syncthreads(); }
.LBB0_1039:
	s_or_b64 exec, exec, s[10:11]
	s_mov_b64 s[10:11], s[0:1]
	s_waitcnt lgkmcnt(0)
	s_barrier
	s_load_dwordx2 s[28:29], s[10:11], 0xc0
	s_mov_b64 s[10:11], s[0:1]
	s_mov_b64 s[12:13], s[0:1]
	s_load_dwordx2 s[10:11], s[10:11], 0xa8
	s_load_dwordx2 s[14:15], s[12:13], 0xb0
	s_mov_b64 s[12:13], s[0:1]
	s_mov_b64 s[16:17], s[0:1]
	s_load_dwordx2 s[12:13], s[12:13], 0xc0
	s_load_dwordx2 s[48:49], s[16:17], 0xc0
	s_mov_b64 s[20:21], s[0:1]
	s_mov_b64 s[16:17], s[0:1]
	s_mov_b64 s[18:19], s[0:1]
	s_load_dwordx2 s[16:17], s[16:17], 0x20
	s_load_dwordx2 s[46:47], s[18:19], 0xc0
	v_mbcnt_lo_u32_b32 v6, -1, 0
	v_mbcnt_hi_u32_b32 v6, -1, v6
	s_movk_i32 s3, 0x2000
	v_or_b32_e32 v0, s69, v6
	v_cmp_gt_i32_e32 vcc, s3, v0
	s_and_saveexec_b64 s[18:19], vcc
	s_cbranch_execz .LBB0_1051
	s_load_dwordx2 s[20:21], s[20:21], 0x18
	v_and_b32_e32 v1, 7, v6
	v_lshlrev_b32_e32 v2, 2, v1
	v_lshl_add_u32 v7, v1, 12, 0
	v_max_i32_e32 v1, 0x1e00, v0
	v_mov_b32_e32 v3, 0
	v_sub_u32_e32 v1, v1, v0
	s_waitcnt lgkmcnt(0)
	v_lshl_add_u64 v[2:3], s[20:21], 0, v[2:3]
	s_mov_b64 s[20:21], 0x1409800
	s_movk_i32 s3, 0x1ff
	v_add_u32_e32 v4, 0x1ff, v1
	v_lshl_add_u64 v[2:3], v[2:3], 0, s[20:21]
	v_ashrrev_i32_e32 v100, 3, v0
	v_mul_u32_u24_e32 v102, 0x5020, v100
	v_mov_b32_e32 v103, 0
	v_lshl_add_u64 v[104:105], v[2:3], 0, v[102:103]
	s_mov_b32 s20, 0x140800
	s_mov_b32 s21, 0
	global_load_dword v110, v[104:105], off
	v_lshl_add_u64 v[104:105], v[104:105], 0, s[20:21]
	global_load_dword v111, v[104:105], off
	v_lshl_add_u64 v[104:105], v[104:105], 0, s[20:21]
	global_load_dword v112, v[104:105], off
	v_lshl_add_u64 v[104:105], v[104:105], 0, s[20:21]
	global_load_dword v113, v[104:105], off
	v_lshl_add_u64 v[104:105], v[104:105], 0, s[20:21]
	global_load_dword v114, v[104:105], off
	v_lshl_add_u64 v[104:105], v[104:105], 0, s[20:21]
	global_load_dword v115, v[104:105], off
	v_lshl_add_u64 v[104:105], v[104:105], 0, s[20:21]
	global_load_dword v116, v[104:105], off
	v_lshl_add_u64 v[104:105], v[104:105], 0, s[20:21]
	global_load_dword v117, v[104:105], off
	v_lshl_add_u64 v[104:105], v[104:105], 0, s[20:21]
	global_load_dword v118, v[104:105], off
	v_lshl_add_u64 v[104:105], v[104:105], 0, s[20:21]
	global_load_dword v119, v[104:105], off
	v_lshl_add_u64 v[104:105], v[104:105], 0, s[20:21]
	global_load_dword v120, v[104:105], off
	v_lshl_add_u64 v[104:105], v[104:105], 0, s[20:21]
	global_load_dword v121, v[104:105], off
	v_lshl_add_u64 v[104:105], v[104:105], 0, s[20:21]
	global_load_dword v122, v[104:105], off
	v_lshl_add_u64 v[104:105], v[104:105], 0, s[20:21]
	global_load_dword v123, v[104:105], off
	v_lshl_add_u64 v[104:105], v[104:105], 0, s[20:21]
	global_load_dword v124, v[104:105], off
	v_lshl_add_u64 v[104:105], v[104:105], 0, s[20:21]
	global_load_dword v125, v[104:105], off
	v_lshl_add_u32 v101, v100, 2, v7
	s_waitcnt vmcnt(15)
	ds_write_b32 v101, v110
	s_waitcnt vmcnt(14)
	ds_write_b32 v101, v111 offset:256
	s_waitcnt vmcnt(13)
	ds_write_b32 v101, v112 offset:512
	s_waitcnt vmcnt(12)
	ds_write_b32 v101, v113 offset:768
	s_waitcnt vmcnt(11)
	ds_write_b32 v101, v114 offset:1024
	s_waitcnt vmcnt(10)
	ds_write_b32 v101, v115 offset:1280
	s_waitcnt vmcnt(9)
	ds_write_b32 v101, v116 offset:1536
	s_waitcnt vmcnt(8)
	ds_write_b32 v101, v117 offset:1792
	s_waitcnt vmcnt(7)
	ds_write_b32 v101, v118 offset:2048
	s_waitcnt vmcnt(6)
	ds_write_b32 v101, v119 offset:2304
	s_waitcnt vmcnt(5)
	ds_write_b32 v101, v120 offset:2560
	s_waitcnt vmcnt(4)
	ds_write_b32 v101, v121 offset:2816
	s_waitcnt vmcnt(3)
	ds_write_b32 v101, v122 offset:3072
	s_waitcnt vmcnt(2)
	ds_write_b32 v101, v123 offset:3328
	s_waitcnt vmcnt(1)
	ds_write_b32 v101, v124 offset:3584
	s_waitcnt vmcnt(0)
	ds_write_b32 v101, v125 offset:3840
